# ctx attention tile: counted vmcnt - V conversion and LDS stores start after the first two loads (vmcnt(2)), K waits for the rest
# speedup vs baseline: 1.0038x; 1.0038x over previous
.LBB0_443:
	v_mov_b32_e32 v59, v129
	v_lshl_add_u64 v[62:63], v[62:63], 0, v[58:59]
	v_mov_b32_e32 v61, v129
	v_lshl_add_u64 v[82:83], v[64:65], 0, v[128:129]
	v_lshl_add_u64 v[62:63], v[62:63], 0, v[60:61]
	global_load_dwordx4 v[64:67], v[82:83], off offset:16
	s_nop 0
	global_load_dwordx4 v[82:85], v[82:83], off
	s_nop 0
	global_load_dwordx4 v[86:89], v[62:63], off offset:64
	global_load_dwordx4 v[90:93], v[62:63], off
	s_mov_b32 s2, s24
	s_add_i32 s24, s24, 1
	s_cmp_lt_u32 s2, 7
	s_cselect_b32 s2, s24, s2
	s_lshl_b32 s3, s2, 5
	s_add_i32 s25, s3, 0xffffff00
	s_cmp_lt_u32 s2, 8
	s_cselect_b32 s3, s3, s25
	s_cmp_gt_u32 s2, 7
	s_waitcnt vmcnt(2)
	v_cvt_pk_bf16_f32 v59, v82, v64
	ds_write_b16 v76, v59 offset:4096
	ds_write_b16_d16_hi v76, v59 offset:4352
	v_cvt_pk_bf16_f32 v59, v83, v65
	ds_write_b16 v76, v59 offset:4160
	ds_write_b16_d16_hi v76, v59 offset:4416
	v_cvt_pk_bf16_f32 v59, v84, v66
	ds_write_b16 v76, v59 offset:4224
	ds_write_b16_d16_hi v76, v59 offset:4480
	v_cvt_pk_bf16_f32 v59, v85, v67
	ds_write_b16 v76, v59 offset:4288
	ds_write_b16_d16_hi v76, v59 offset:4544
	s_waitcnt vmcnt(0)
	v_cvt_pk_bf16_f32 v63, v92, v93
	v_cvt_pk_bf16_f32 v62, v90, v91
	ds_write_b64 v74, v[62:63]
	v_cvt_pk_bf16_f32 v63, v88, v89
	v_cvt_pk_bf16_f32 v62, v86, v87
	ds_write_b64 v75, v[62:63]
	v_add_u32_e32 v66, s3, v73
	s_mov_b64 s[2:3], -1
	s_waitcnt lgkmcnt(0)
	s_barrier
	s_cbranch_scc0 .LBB0_445
	v_ashrrev_i32_e32 v67, 31, v66
	v_lshl_add_u64 v[62:63], v[66:67], 0, v[54:55]
	v_lshlrev_b64 v[64:65], 9, v[62:63]
	v_readlane_b32 s68, v253, 56
	v_lshl_or_b32 v64, v52, 2, v64
	v_readlane_b32 s74, v253, 62
	v_readlane_b32 s75, v253, 63
	v_readlane_b32 s76, v254, 0
	v_readlane_b32 s77, v254, 1
	v_readlane_b32 s69, v253, 57
	v_readlane_b32 s70, v253, 58
	v_readlane_b32 s71, v253, 59
	v_readlane_b32 s72, v253, 60
	v_readlane_b32 s73, v253, 61
	v_readlane_b32 s78, v254, 2
	v_readlane_b32 s79, v254, 3
	v_readlane_b32 s80, v254, 4
	v_readlane_b32 s81, v254, 5
	v_readlane_b32 s82, v254, 6
	v_readlane_b32 s83, v254, 7
	v_lshl_add_u64 v[62:63], s[74:75], 0, v[64:65]
	v_lshl_add_u64 v[64:65], s[76:77], 0, v[64:65]
	s_mov_b64 s[2:3], 0
